# previous + hand-written layer-1 weight conversion (16B loads, LDS transpose double-buffered, prefetch, column-tile-fastest order)
# speedup vs baseline: 1.0445x; 1.0110x over previous
; DI int ltid() { int t = __builtin_amdgcn_workitem_id_x(); asm volatile("" : "+v"(t)); return t; }
; template <int MAPK>
; DI void wconv_tile(const float* __restrict__ W, int K, int Nsrc, u16* __restrict__ Wt, int kt, int nt,
;                            char* smem) {
;   float* tile = (float*)smem;
;   const int tid = ltid();
;   const int n = tid & 63;
;   const int nd = nt * 64 + n;
;   const int src = (MAPK == 1) ? map_in(nd) : (MAPK == 2 ? map_13(nd) : nd);
; DI void wconv_item(const Params& p, int l, int t, char* smem) {
;   u16* wt = (u16*)(p.ws + OFF_WT);
;   if (t < WC_T_IN) { wconv_tile<1>(p.w_in + (size_t)l * 1024 * WIN, 1024, WIN, wt + WT_IN, t % 16, t / 16, smem); return; }
;   t -= WC_T_IN;
;   if (t < WC_T_A) { wconv_tile<0>(p.w_branch_a + (size_t)l * 1024 * 1024, 1024, 1024, wt + WT_A, t % 16, t / 16, smem); return; }
;   t -= WC_T_A;
;   if (t < WC_T_B) { wconv_tile<0>(p.w_branch_b + (size_t)l * 512 * 1024, 512, 1024, wt + WT_B, t % 8, t / 8, smem); return; }
;   t -= WC_T_B;
;   if (t < WC_T_OUT) { wconv_tile<0>(p.w_out + (size_t)l * 1024 * 1024, 1024, 1024, wt + WT_OUT, t % 16, t / 16, smem); return; }
;   t -= WC_T_OUT;
;   if (t < WC_T_13) { wconv_tile<2>(p.ffn_w13 + (size_t)l * 1024 * 5632, 1024, 5632, wt + WT_13, t % 16, t / 16, smem); return; }
;   t -= WC_T_13;
;   if (t < WC_T_2) { wconv_tile<0>(p.ffn_w2 + (size_t)l * FFN * 1024, FFN, 1024, wt + WT_2, t % 44, t / 44, smem); return; }
;   t -= WC_T_2;
;   wconv_tile<0>(p.rwkv_g2 + (size_t)l * 128 * 512, 128, 512, wt + WT_G2, t % 2, t / 2, smem);
; }
.LBB0_781:
	s_or_b64 exec, exec, s[0:1]
	v_readlane_b32 s0, v243, 7
	s_cmp_lt_u32 s0, 12
	v_readlane_b32 s4, v243, 5
	s_cselect_b64 s[0:1], -1, 0
	v_readlane_b32 s5, v243, 6
	s_or_b64 s[0:1], s[4:5], s[0:1]
	s_and_b64 vcc, exec, s[0:1]
	s_cbranch_vccnz .LBB0_814
	v_writelane_b32 v255, s0, 0
	v_writelane_b32 v255, s1, 1
	v_writelane_b32 v255, s2, 2
	v_writelane_b32 v255, s3, 3
	v_writelane_b32 v255, s4, 4
	v_writelane_b32 v255, s5, 5
	v_writelane_b32 v255, s6, 6
	v_writelane_b32 v255, s7, 7
	v_writelane_b32 v255, s8, 8
	v_writelane_b32 v255, s9, 9
	v_writelane_b32 v255, s10, 10
	v_writelane_b32 v255, s11, 11
	v_writelane_b32 v255, s12, 12
	v_writelane_b32 v255, s13, 13
	v_writelane_b32 v255, s14, 14
	v_writelane_b32 v255, s15, 15
	v_writelane_b32 v255, s16, 16
	v_writelane_b32 v255, s17, 17
	v_writelane_b32 v255, s18, 18
	v_writelane_b32 v255, s19, 19
	v_writelane_b32 v255, s20, 20
	v_writelane_b32 v255, s21, 21
	v_writelane_b32 v255, s22, 22
	v_writelane_b32 v255, s23, 23
	v_writelane_b32 v255, s24, 24
	v_writelane_b32 v255, s25, 25
	v_writelane_b32 v255, s26, 26
	v_writelane_b32 v255, s27, 27
	v_writelane_b32 v255, s28, 28
	v_writelane_b32 v255, s29, 29
	v_writelane_b32 v255, s30, 30
	v_writelane_b32 v255, s31, 31
	v_writelane_b32 v255, s32, 32
	v_writelane_b32 v255, s33, 33
	v_writelane_b32 v255, s34, 34
	v_writelane_b32 v255, s35, 35
	v_writelane_b32 v255, s36, 36
	v_writelane_b32 v255, s37, 37
	v_writelane_b32 v255, s38, 38
	v_writelane_b32 v255, s39, 39
	v_writelane_b32 v255, s40, 40
	v_writelane_b32 v255, s41, 41
	v_writelane_b32 v255, s42, 42
	v_writelane_b32 v255, s43, 43
	v_writelane_b32 v255, s44, 44
	v_writelane_b32 v255, s45, 45
	v_writelane_b32 v255, s46, 46
	v_writelane_b32 v255, s47, 47
	v_writelane_b32 v255, s48, 48
	v_writelane_b32 v255, s49, 49
	v_writelane_b32 v255, s50, 50
	v_writelane_b32 v255, s51, 51
	v_writelane_b32 v255, s52, 52
	v_writelane_b32 v255, s53, 53
	v_writelane_b32 v255, s54, 54
	v_writelane_b32 v255, s55, 55
	v_writelane_b32 v255, s56, 56
	v_writelane_b32 v255, s57, 57
	v_writelane_b32 v255, s58, 58
	v_writelane_b32 v255, s59, 59
	v_writelane_b32 v255, s60, 60
	v_writelane_b32 v255, s61, 61
	v_writelane_b32 v255, s62, 62
	v_writelane_b32 v255, s63, 63
	v_writelane_b32 v254, s64, 0
	v_writelane_b32 v254, s65, 1
	v_writelane_b32 v254, s66, 2
	v_writelane_b32 v254, s67, 3
	v_writelane_b32 v254, s68, 4
	v_writelane_b32 v254, s69, 5
	v_writelane_b32 v254, s70, 6
	v_writelane_b32 v254, s71, 7
	v_writelane_b32 v254, s72, 8
	v_writelane_b32 v254, s73, 9
	v_writelane_b32 v254, s74, 10
	v_writelane_b32 v254, s75, 11
	v_writelane_b32 v254, s76, 12
	v_writelane_b32 v254, s77, 13
	v_writelane_b32 v254, s78, 14
	v_writelane_b32 v254, s79, 15
	v_writelane_b32 v254, s80, 16
	v_writelane_b32 v254, s81, 17
	v_writelane_b32 v254, s82, 18
	v_writelane_b32 v254, s83, 19
	v_writelane_b32 v254, s84, 20
	v_writelane_b32 v254, s85, 21
	v_readlane_b32 s4, v246, 4
	v_readlane_b32 s5, v246, 5
	v_readlane_b32 s22, v244, 54
	v_readlane_b32 s23, v243, 8
	s_sub_u32 s4, s4, 0xe8
	s_subb_u32 s5, s5, 0
	s_load_dwordx2 s[6:7], s[4:5], 0x40
	s_load_dwordx2 s[8:9], s[4:5], 0xa8
	s_load_dwordx2 s[10:11], s[4:5], 0xb0
	s_load_dwordx2 s[12:13], s[4:5], 0xb8
	s_load_dwordx2 s[14:15], s[4:5], 0xc0
	s_load_dwordx2 s[16:17], s[4:5], 0xc8
	s_load_dwordx2 s[18:19], s[4:5], 0x80
	s_load_dwordx2 s[20:21], s[4:5], 0xe0
	s_mov_b32 s24, 1
	v_and_b32_e32 v76, 0xff, v196
	v_lshrrev_b32_e32 v62, 4, v76
	v_and_b32_e32 v63, 15, v76
	v_lshrrev_b32_e32 v77, 2, v63
	v_and_b32_e32 v75, 3, v63
	v_lshlrev_b32_e32 v75, 4, v75
	v_cmp_eq_u32_e32 vcc, 1, v77
	s_nop 1
	v_cndmask_b32_e64 v64, 0, 1, vcc
	v_cmp_eq_u32_e32 vcc, 2, v77
	s_nop 1
	v_cndmask_b32_e64 v65, 0, 1, vcc
	v_cmp_eq_u32_e32 vcc, 3, v77
	s_nop 1
	v_cndmask_b32_e64 v66, 0, 1, vcc
	v_mul_u32_u24_e32 v67, 272, v62
	v_lshl_add_u32 v67, v63, 4, v67
	v_and_b32_e32 v69, 63, v76
	v_lshrrev_b32_e32 v77, 6, v76
	v_lshlrev_b32_e32 v70, 5, v77
	v_mul_u32_u24_e32 v68, 4352, v77
	v_lshl_add_u32 v68, v69, 2, v68
	s_waitcnt lgkmcnt(0)
	s_cmp_lt_u32 s22, 4528
	s_cbranch_scc0 .Lwc_exit
	s_barrier
	s_mov_b32 s46, 0
	s_mov_b32 s47, 1024
	s_mov_b32 s48, 7040
	s_mov_b32 s49, 0
	s_mov_b32 s50, 1
	s_mov_b32 s51, 0
	s_mov_b64 s[52:53], s[6:7]
	s_cmp_ge_u32 s22, 1760
	s_cselect_b32 s46, 1760, s46
	s_cselect_b32 s47, 1024, s47
	s_cselect_b32 s48, 1024, s48
	s_cselect_b32 s49, 7208960, s49
	s_cselect_b32 s50, 0, s50
	s_cselect_b32 s51, 1, s51
	s_cselect_b64 s[52:53], s[8:9], s[52:53]
	s_cmp_ge_u32 s22, 2016
	s_cselect_b32 s46, 2016, s46
	s_cselect_b32 s47, 512, s47
	s_cselect_b32 s48, 1024, s48
	s_cselect_b32 s49, 8257536, s49
	s_cselect_b32 s50, 0, s50
	s_cselect_b32 s51, 2, s51
	s_cselect_b64 s[52:53], s[10:11], s[52:53]
	s_cmp_ge_u32 s22, 2144
	s_cselect_b32 s46, 2144, s46
	s_cselect_b32 s47, 1024, s47
	s_cselect_b32 s48, 1024, s48
	s_cselect_b32 s49, 8781824, s49
	s_cselect_b32 s50, 0, s50
	s_cselect_b32 s51, 3, s51
	s_cselect_b64 s[52:53], s[12:13], s[52:53]
	s_cmp_ge_u32 s22, 2400
	s_cselect_b32 s46, 2400, s46
	s_cselect_b32 s47, 1024, s47
	s_cselect_b32 s48, 5632, s48
	s_cselect_b32 s49, 9830400, s49
	s_cselect_b32 s50, 2, s50
	s_cselect_b32 s51, 4, s51
	s_cselect_b64 s[52:53], s[14:15], s[52:53]
	s_cmp_ge_u32 s22, 3808
	s_cselect_b32 s46, 3808, s46
	s_cselect_b32 s47, 2816, s47
	s_cselect_b32 s48, 1024, s48
	s_cselect_b32 s49, 15597568, s49
	s_cselect_b32 s50, 0, s50
	s_cselect_b32 s51, 5, s51
	s_cselect_b64 s[52:53], s[16:17], s[52:53]
	s_cmp_ge_u32 s22, 4512
	s_cselect_b32 s46, 4512, s46
	s_cselect_b32 s47, 128, s47
	s_cselect_b32 s48, 512, s48
	s_cselect_b32 s49, 18481152, s49
	s_cselect_b32 s50, 0, s50
; DI int ltid() { int t = __builtin_amdgcn_workitem_id_x(); asm volatile("" : "+v"(t)); return t; }
; template <int MAPK>
; DI void wconv_tile(const float* __restrict__ W, int K, int Nsrc, u16* __restrict__ Wt, int kt, int nt,
;                            char* smem) {
;   float* tile = (float*)smem;
;   const int tid = ltid();
;   const int n = tid & 63;
;   const int nd = nt * 64 + n;
;   const int src = (MAPK == 1) ? map_in(nd) : (MAPK == 2 ? map_13(nd) : nd);
;   __syncthreads();
; #pragma unroll
;   for (int i = 0; i < 16; ++i) {
;     int k = i * 4 + (tid >> 6);
;     tile[k * 65 + n] = W[(size_t)(kt * 64 + k) * Nsrc + src];
	s_cselect_b32 s51, 6, s51
	s_cselect_b64 s[52:53], s[18:19], s[52:53]
	s_sub_u32 s46, s22, s46
	s_mov_b32 s54, 9533
	s_mov_b32 s55, 110
	s_cmp_eq_u32 s51, 1
	s_cselect_b32 s54, 65536, s54
	s_cselect_b32 s55, 16, s55
	s_cmp_eq_u32 s51, 2
	s_cselect_b32 s54, 65536, s54
	s_cselect_b32 s55, 16, s55
	s_cmp_eq_u32 s51, 3
	s_cselect_b32 s54, 65536, s54
	s_cselect_b32 s55, 16, s55
	s_cmp_eq_u32 s51, 4
	s_cselect_b32 s54, 11916, s54
	s_cselect_b32 s55, 88, s55
	s_cmp_eq_u32 s51, 5
	s_cselect_b32 s54, 65536, s54
	s_cselect_b32 s55, 16, s55
	s_cmp_eq_u32 s51, 6
	s_cselect_b32 s54, 131072, s54
	s_cselect_b32 s55, 8, s55
	s_mul_i32 s56, s46, s54
	s_lshr_b32 s56, s56, 20
	s_mul_i32 s55, s56, s55
	s_sub_u32 s55, s46, s55
	s_lshl_b32 s28, s48, 2
	s_lshl_b32 s32, s47, 1
	s_mul_i32 s46, s47, s48
	s_mul_i32 s46, s46, s24
	s_lshl_b32 s57, s56, 6
	s_mul_i32 s57, s57, s48
	s_add_u32 s46, s46, s57
	s_lshl_b32 s46, s46, 2
	s_add_u32 s26, s52, s46
	s_addc_u32 s27, s53, 0
	s_lshl_b32 s46, s55, 6
	s_mul_i32 s46, s46, s47
	s_lshl_b32 s57, s56, 6
	s_add_u32 s46, s46, s57
	s_add_u32 s46, s46, s49
	s_lshl_b32 s46, s46, 1
	s_add_u32 s30, s20, s46
	s_addc_u32 s31, s21, 0
	s_lshl_b32 s46, s55, 8
	s_add_u32 s42, s46, 0
	s_add_u32 s43, s46, 64
	s_add_u32 s44, s46, 128
	s_add_u32 s45, s46, 192
	s_cmp_lt_u32 s55, 16
	s_cselect_b32 s57, 1, 0
	s_and_b32 s57, s57, s50
	s_cmp_eq_u32 s57, 1
	s_cselect_b32 s56, s44, s43
	s_cselect_b32 s44, s43, s44
	s_mov_b32 s43, s56
	s_lshl_b32 s46, s55, 7
	s_add_u32 s56, s46, 64
	s_add_u32 s57, s46, 11264
	s_cmp_eq_u32 s50, 2
	s_cselect_b32 s42, s46, s42
	s_cselect_b32 s43, s56, s43
	s_cselect_b32 s44, s57, s44
	s_add_u32 s57, s57, 64
	s_cmp_eq_u32 s50, 2
	s_cselect_b32 s45, s57, s45
	v_mul_u32_u24_e32 v71, s28, v62
	v_add_u32_e32 v71, s42, v71
	s_sub_u32 s46, s43, s42
	s_sub_u32 s47, s44, s42
	s_sub_u32 s48, s45, s42
	v_mad_u32_u24 v71, v64, s46, v71
	v_mad_u32_u24 v71, v65, s47, v71
	v_mad_u32_u24 v71, v66, s48, v71
	v_add_u32_e32 v71, v71, v75
	s_lshl_b32 s46, s28, 4
	s_mov_b64 s[58:59], s[26:27]
	s_add_u32 s60, s58, s46
	s_addc_u32 s61, s59, 0
	s_add_u32 s62, s60, s46
	s_addc_u32 s63, s61, 0
	s_add_u32 s64, s62, s46
	s_addc_u32 s65, s63, 0
	global_load_dwordx4 v[6:9], v71, s[58:59]
	global_load_dwordx4 v[10:13], v71, s[60:61]
	global_load_dwordx4 v[14:17], v71, s[62:63]
	global_load_dwordx4 v[18:21], v71, s[64:65]
.Lwc_loop:
	s_add_u32 s25, s22, s23
	s_cmp_lt_u32 s25, 4528
	s_cbranch_scc0 .Lwc_last0
	s_mov_b32 s46, 0
	s_mov_b32 s47, 1024
	s_mov_b32 s48, 7040
	s_mov_b32 s49, 0
	s_mov_b32 s50, 1
	s_mov_b32 s51, 0
	s_mov_b64 s[52:53], s[6:7]
	s_cmp_ge_u32 s25, 1760
	s_cselect_b32 s46, 1760, s46
	s_cselect_b32 s47, 1024, s47
	s_cselect_b32 s48, 1024, s48
	s_cselect_b32 s49, 7208960, s49
	s_cselect_b32 s50, 0, s50
	s_cselect_b32 s51, 1, s51
	s_cselect_b64 s[52:53], s[8:9], s[52:53]
	s_cmp_ge_u32 s25, 2016
	s_cselect_b32 s46, 2016, s46
	s_cselect_b32 s47, 512, s47
	s_cselect_b32 s48, 1024, s48
	s_cselect_b32 s49, 8257536, s49
	s_cselect_b32 s50, 0, s50
	s_cselect_b32 s51, 2, s51
	s_cselect_b64 s[52:53], s[10:11], s[52:53]
	s_cmp_ge_u32 s25, 2144
	s_cselect_b32 s46, 2144, s46
	s_cselect_b32 s47, 1024, s47
	s_cselect_b32 s48, 1024, s48
	s_cselect_b32 s49, 8781824, s49
	s_cselect_b32 s50, 0, s50
	s_cselect_b32 s51, 3, s51
	s_cselect_b64 s[52:53], s[12:13], s[52:53]
	s_cmp_ge_u32 s25, 2400
	s_cselect_b32 s46, 2400, s46
	s_cselect_b32 s47, 1024, s47
	s_cselect_b32 s48, 5632, s48
	s_cselect_b32 s49, 9830400, s49
	s_cselect_b32 s50, 2, s50
	s_cselect_b32 s51, 4, s51
	s_cselect_b64 s[52:53], s[14:15], s[52:53]
	s_cmp_ge_u32 s25, 3808
	s_cselect_b32 s46, 3808, s46
	s_cselect_b32 s47, 2816, s47
	s_cselect_b32 s48, 1024, s48
	s_cselect_b32 s49, 15597568, s49
	s_cselect_b32 s50, 0, s50
	s_cselect_b32 s51, 5, s51
	s_cselect_b64 s[52:53], s[16:17], s[52:53]
	s_cmp_ge_u32 s25, 4512
	s_cselect_b32 s46, 4512, s46
	s_cselect_b32 s47, 128, s47
	s_cselect_b32 s48, 512, s48
	s_cselect_b32 s49, 18481152, s49
	s_cselect_b32 s50, 0, s50
	s_cselect_b32 s51, 6, s51
	s_cselect_b64 s[52:53], s[18:19], s[52:53]
	s_sub_u32 s46, s25, s46
	s_mov_b32 s54, 9533
	s_mov_b32 s55, 110
	s_cmp_eq_u32 s51, 1
	s_cselect_b32 s54, 65536, s54
	s_cselect_b32 s55, 16, s55
	s_cmp_eq_u32 s51, 2
	s_cselect_b32 s54, 65536, s54
	s_cselect_b32 s55, 16, s55
	s_cmp_eq_u32 s51, 3
	s_cselect_b32 s54, 65536, s54
	s_cselect_b32 s55, 16, s55
	s_cmp_eq_u32 s51, 4
	s_cselect_b32 s54, 11916, s54
	s_cselect_b32 s55, 88, s55
	s_cmp_eq_u32 s51, 5
	s_cselect_b32 s54, 65536, s54
	s_cselect_b32 s55, 16, s55
	s_cmp_eq_u32 s51, 6
	s_cselect_b32 s54, 131072, s54
	s_cselect_b32 s55, 8, s55
	s_mul_i32 s56, s46, s54
	s_lshr_b32 s56, s56, 20
	s_mul_i32 s55, s56, s55
	s_sub_u32 s55, s46, s55
	s_lshl_b32 s36, s48, 2
	s_lshl_b32 s40, s47, 1
	s_mul_i32 s46, s47, s48
	s_mul_i32 s46, s46, s24
	s_lshl_b32 s57, s56, 6
	s_mul_i32 s57, s57, s48
	s_add_u32 s46, s46, s57
	s_lshl_b32 s46, s46, 2
	s_add_u32 s34, s52, s46
	s_addc_u32 s35, s53, 0
	s_lshl_b32 s46, s55, 6
	s_mul_i32 s46, s46, s47
	s_lshl_b32 s57, s56, 6
	s_add_u32 s46, s46, s57
	s_add_u32 s46, s46, s49
	s_lshl_b32 s46, s46, 1
	s_add_u32 s38, s20, s46
	s_addc_u32 s39, s21, 0
	s_lshl_b32 s46, s55, 8
	s_add_u32 s42, s46, 0
	s_add_u32 s43, s46, 64
	s_add_u32 s44, s46, 128
	s_add_u32 s45, s46, 192
	s_cmp_lt_u32 s55, 16
	s_cselect_b32 s57, 1, 0
	s_and_b32 s57, s57, s50
	s_cmp_eq_u32 s57, 1
	s_cselect_b32 s56, s44, s43
	s_cselect_b32 s44, s43, s44
	s_mov_b32 s43, s56
	s_lshl_b32 s46, s55, 7
	s_add_u32 s56, s46, 64
	s_add_u32 s57, s46, 11264
	s_cmp_eq_u32 s50, 2
	s_cselect_b32 s42, s46, s42
	s_cselect_b32 s43, s56, s43
	s_cselect_b32 s44, s57, s44
	s_add_u32 s57, s57, 64
	s_cmp_eq_u32 s50, 2
	s_cselect_b32 s45, s57, s45
	v_mul_u32_u24_e32 v72, s36, v62
	v_add_u32_e32 v72, s42, v72
	s_sub_u32 s46, s43, s42
	s_sub_u32 s47, s44, s42
	s_sub_u32 s48, s45, s42
	v_mad_u32_u24 v72, v64, s46, v72
	v_mad_u32_u24 v72, v65, s47, v72
	v_mad_u32_u24 v72, v66, s48, v72
	v_add_u32_e32 v72, v72, v75
	s_lshl_b32 s46, s36, 4
	s_mov_b64 s[58:59], s[34:35]
	s_add_u32 s60, s58, s46
	s_addc_u32 s61, s59, 0
	s_add_u32 s62, s60, s46
	s_addc_u32 s63, s61, 0
	s_add_u32 s64, s62, s46
	s_addc_u32 s65, s63, 0
	global_load_dwordx4 v[22:25], v72, s[58:59]
	global_load_dwordx4 v[26:29], v72, s[60:61]
	global_load_dwordx4 v[30:33], v72, s[62:63]
	global_load_dwordx4 v[34:37], v72, s[64:65]
	s_waitcnt vmcnt(4)
	ds_write_b128 v67, v[6:9] offset:0
	ds_write_b128 v67, v[10:13] offset:4352
	ds_write_b128 v67, v[14:17] offset:8704
	ds_write_b128 v67, v[18:21] offset:13056
	s_waitcnt lgkmcnt(0)
	s_barrier
; DI unsigned pack2(float a, float b) { f32x2_t v = {a, b}; bf16x2_t r = __builtin_convertvector(v, bf16x2_t); return __builtin_bit_cast(unsigned, r); }
; template <int MAPK>
; DI void wconv_tile(const float* __restrict__ W, int K, int Nsrc, u16* __restrict__ Wt, int kt, int nt,
;                            char* smem) {
;     ...
;   __syncthreads();
; #pragma unroll
;   for (int i = 0; i < 16; ++i) {
;     int k = i * 4 + (tid >> 6);
;     tile[k * 65 + n] = W[(size_t)(kt * 64 + k) * Nsrc + src];
;   }
;   __syncthreads();
; #pragma unroll
;   for (int j = 0; j < 2; ++j) {
;     int nn = (tid >> 3) + 32 * j, cch = tid & 7;
;     unsigned pk[4];
; #pragma unroll
;     for (int i = 0; i < 4; ++i) pk[i] = pack2(tile[(cch * 8 + 2 * i) * 65 + nn], tile[(cch * 8 + 2 * i + 1) * 65 + nn]);
;     *(u32x4*)(Wt + (size_t)(nt * 64 + nn) * K + kt * 64 + cch * 8) = mk4(pk[0], pk[1], pk[2], pk[3]);
;   }
	ds_read_b32 v38, v68 offset:0
	ds_read_b32 v39, v68 offset:272
	ds_read_b32 v40, v68 offset:544
	ds_read_b32 v41, v68 offset:816
	ds_read_b32 v42, v68 offset:1088
	ds_read_b32 v43, v68 offset:1360
	ds_read_b32 v44, v68 offset:1632
	ds_read_b32 v45, v68 offset:1904
	ds_read_b32 v46, v68 offset:2176
	ds_read_b32 v47, v68 offset:2448
	ds_read_b32 v48, v68 offset:2720
	ds_read_b32 v49, v68 offset:2992
	ds_read_b32 v50, v68 offset:3264
	ds_read_b32 v51, v68 offset:3536
	ds_read_b32 v52, v68 offset:3808
	ds_read_b32 v53, v68 offset:4080
	v_mul_u32_u24_e32 v73, s32, v69
	v_add_u32_e32 v73, v73, v70
	s_waitcnt lgkmcnt(0)
	v_cvt_pk_bf16_f32 v54, v38, v39
	v_cvt_pk_bf16_f32 v55, v40, v41
	v_cvt_pk_bf16_f32 v56, v42, v43
	v_cvt_pk_bf16_f32 v57, v44, v45
	v_cvt_pk_bf16_f32 v58, v46, v47
	v_cvt_pk_bf16_f32 v59, v48, v49
	v_cvt_pk_bf16_f32 v60, v50, v51
	v_cvt_pk_bf16_f32 v61, v52, v53
	global_store_dwordx4 v73, v[54:57], s[30:31]
	global_store_dwordx4 v73, v[58:61], s[30:31] offset:16
	s_mov_b32 s22, s25
	s_add_u32 s25, s22, s23
	s_cmp_lt_u32 s25, 4528
	s_cbranch_scc0 .Lwc_last1
	s_mov_b32 s46, 0
	s_mov_b32 s47, 1024
	s_mov_b32 s48, 7040
	s_mov_b32 s49, 0
	s_mov_b32 s50, 1
	s_mov_b32 s51, 0
	s_mov_b64 s[52:53], s[6:7]
	s_cmp_ge_u32 s25, 1760
	s_cselect_b32 s46, 1760, s46
	s_cselect_b32 s47, 1024, s47
	s_cselect_b32 s48, 1024, s48
	s_cselect_b32 s49, 7208960, s49
	s_cselect_b32 s50, 0, s50
	s_cselect_b32 s51, 1, s51
	s_cselect_b64 s[52:53], s[8:9], s[52:53]
	s_cmp_ge_u32 s25, 2016
	s_cselect_b32 s46, 2016, s46
	s_cselect_b32 s47, 512, s47
	s_cselect_b32 s48, 1024, s48
	s_cselect_b32 s49, 8257536, s49
	s_cselect_b32 s50, 0, s50
	s_cselect_b32 s51, 2, s51
	s_cselect_b64 s[52:53], s[10:11], s[52:53]
	s_cmp_ge_u32 s25, 2144
	s_cselect_b32 s46, 2144, s46
	s_cselect_b32 s47, 1024, s47
	s_cselect_b32 s48, 1024, s48
	s_cselect_b32 s49, 8781824, s49
	s_cselect_b32 s50, 0, s50
	s_cselect_b32 s51, 3, s51
	s_cselect_b64 s[52:53], s[12:13], s[52:53]
	s_cmp_ge_u32 s25, 2400
	s_cselect_b32 s46, 2400, s46
	s_cselect_b32 s47, 1024, s47
	s_cselect_b32 s48, 5632, s48
	s_cselect_b32 s49, 9830400, s49
	s_cselect_b32 s50, 2, s50
	s_cselect_b32 s51, 4, s51
	s_cselect_b64 s[52:53], s[14:15], s[52:53]
	s_cmp_ge_u32 s25, 3808
	s_cselect_b32 s46, 3808, s46
	s_cselect_b32 s47, 2816, s47
	s_cselect_b32 s48, 1024, s48
	s_cselect_b32 s49, 15597568, s49
	s_cselect_b32 s50, 0, s50
	s_cselect_b32 s51, 5, s51
	s_cselect_b64 s[52:53], s[16:17], s[52:53]
	s_cmp_ge_u32 s25, 4512
	s_cselect_b32 s46, 4512, s46
	s_cselect_b32 s47, 128, s47
	s_cselect_b32 s48, 512, s48
	s_cselect_b32 s49, 18481152, s49
	s_cselect_b32 s50, 0, s50
	s_cselect_b32 s51, 6, s51
	s_cselect_b64 s[52:53], s[18:19], s[52:53]
	s_sub_u32 s46, s25, s46
	s_mov_b32 s54, 9533
	s_mov_b32 s55, 110
	s_cmp_eq_u32 s51, 1
	s_cselect_b32 s54, 65536, s54
	s_cselect_b32 s55, 16, s55
	s_cmp_eq_u32 s51, 2
	s_cselect_b32 s54, 65536, s54
	s_cselect_b32 s55, 16, s55
	s_cmp_eq_u32 s51, 3
	s_cselect_b32 s54, 65536, s54
	s_cselect_b32 s55, 16, s55
	s_cmp_eq_u32 s51, 4
	s_cselect_b32 s54, 11916, s54
	s_cselect_b32 s55, 88, s55
	s_cmp_eq_u32 s51, 5
	s_cselect_b32 s54, 65536, s54
	s_cselect_b32 s55, 16, s55
	s_cmp_eq_u32 s51, 6
	s_cselect_b32 s54, 131072, s54
	s_cselect_b32 s55, 8, s55
	s_mul_i32 s56, s46, s54
	s_lshr_b32 s56, s56, 20
	s_mul_i32 s55, s56, s55
	s_sub_u32 s55, s46, s55
	s_lshl_b32 s28, s48, 2
	s_lshl_b32 s32, s47, 1
	s_mul_i32 s46, s47, s48
	s_mul_i32 s46, s46, s24
	s_lshl_b32 s57, s56, 6
	s_mul_i32 s57, s57, s48
	s_add_u32 s46, s46, s57
	s_lshl_b32 s46, s46, 2
	s_add_u32 s26, s52, s46
	s_addc_u32 s27, s53, 0
	s_lshl_b32 s46, s55, 6
	s_mul_i32 s46, s46, s47
	s_lshl_b32 s57, s56, 6
	s_add_u32 s46, s46, s57
	s_add_u32 s46, s46, s49
	s_lshl_b32 s46, s46, 1
	s_add_u32 s30, s20, s46
	s_addc_u32 s31, s21, 0
	s_lshl_b32 s46, s55, 8
	s_add_u32 s42, s46, 0
	s_add_u32 s43, s46, 64
	s_add_u32 s44, s46, 128
	s_add_u32 s45, s46, 192
	s_cmp_lt_u32 s55, 16
	s_cselect_b32 s57, 1, 0
	s_and_b32 s57, s57, s50
	s_cmp_eq_u32 s57, 1
	s_cselect_b32 s56, s44, s43
	s_cselect_b32 s44, s43, s44
	s_mov_b32 s43, s56
	s_lshl_b32 s46, s55, 7
	s_add_u32 s56, s46, 64
	s_add_u32 s57, s46, 11264
	s_cmp_eq_u32 s50, 2
	s_cselect_b32 s42, s46, s42
	s_cselect_b32 s43, s56, s43
	s_cselect_b32 s44, s57, s44
	s_add_u32 s57, s57, 64
	s_cmp_eq_u32 s50, 2
	s_cselect_b32 s45, s57, s45
	v_mul_u32_u24_e32 v71, s28, v62
	v_add_u32_e32 v71, s42, v71
	s_sub_u32 s46, s43, s42
	s_sub_u32 s47, s44, s42
	s_sub_u32 s48, s45, s42
	v_mad_u32_u24 v71, v64, s46, v71
	v_mad_u32_u24 v71, v65, s47, v71
	v_mad_u32_u24 v71, v66, s48, v71
	v_add_u32_e32 v71, v71, v75
	s_lshl_b32 s46, s28, 4
	s_mov_b64 s[58:59], s[26:27]
	s_add_u32 s60, s58, s46
	s_addc_u32 s61, s59, 0
	s_add_u32 s62, s60, s46
	s_addc_u32 s63, s61, 0
	s_add_u32 s64, s62, s46
	s_addc_u32 s65, s63, 0
	global_load_dwordx4 v[6:9], v71, s[58:59]
	global_load_dwordx4 v[10:13], v71, s[60:61]
	global_load_dwordx4 v[14:17], v71, s[62:63]
	global_load_dwordx4 v[18:21], v71, s[64:65]
	s_waitcnt vmcnt(4)
	ds_write_b128 v67, v[22:25] offset:17408
	ds_write_b128 v67, v[26:29] offset:21760
	ds_write_b128 v67, v[30:33] offset:26112
	ds_write_b128 v67, v[34:37] offset:30464
	s_waitcnt lgkmcnt(0)
	s_barrier
	ds_read_b32 v38, v68 offset:17408
	ds_read_b32 v39, v68 offset:17680
	ds_read_b32 v40, v68 offset:17952
	ds_read_b32 v41, v68 offset:18224
	ds_read_b32 v42, v68 offset:18496
	ds_read_b32 v43, v68 offset:18768
	ds_read_b32 v44, v68 offset:19040
	ds_read_b32 v45, v68 offset:19312
	ds_read_b32 v46, v68 offset:19584
	ds_read_b32 v47, v68 offset:19856
	ds_read_b32 v48, v68 offset:20128
	ds_read_b32 v49, v68 offset:20400
	ds_read_b32 v50, v68 offset:20672
	ds_read_b32 v51, v68 offset:20944
	ds_read_b32 v52, v68 offset:21216
	ds_read_b32 v53, v68 offset:21488
	v_mul_u32_u24_e32 v73, s40, v69
	v_add_u32_e32 v73, v73, v70
	s_waitcnt lgkmcnt(0)
	v_cvt_pk_bf16_f32 v54, v38, v39
	v_cvt_pk_bf16_f32 v55, v40, v41
	v_cvt_pk_bf16_f32 v56, v42, v43
	v_cvt_pk_bf16_f32 v57, v44, v45
	v_cvt_pk_bf16_f32 v58, v46, v47
	v_cvt_pk_bf16_f32 v59, v48, v49
	v_cvt_pk_bf16_f32 v60, v50, v51
	v_cvt_pk_bf16_f32 v61, v52, v53
	global_store_dwordx4 v73, v[54:57], s[38:39]
	global_store_dwordx4 v73, v[58:61], s[38:39] offset:16
	s_mov_b32 s22, s25
	s_branch .Lwc_loop
; DI unsigned pack2(float a, float b) { f32x2_t v = {a, b}; bf16x2_t r = __builtin_convertvector(v, bf16x2_t); return __builtin_bit_cast(unsigned, r); }
; template <int MAPK>
; DI void wconv_tile(const float* __restrict__ W, int K, int Nsrc, u16* __restrict__ Wt, int kt, int nt,
;                            char* smem) {
;     ...
;   __syncthreads();
; #pragma unroll
;   for (int i = 0; i < 16; ++i) {
;     int k = i * 4 + (tid >> 6);
;     tile[k * 65 + n] = W[(size_t)(kt * 64 + k) * Nsrc + src];
;   }
;   __syncthreads();
; #pragma unroll
;   for (int j = 0; j < 2; ++j) {
;     int nn = (tid >> 3) + 32 * j, cch = tid & 7;
;     unsigned pk[4];
; #pragma unroll
;     for (int i = 0; i < 4; ++i) pk[i] = pack2(tile[(cch * 8 + 2 * i) * 65 + nn], tile[(cch * 8 + 2 * i + 1) * 65 + nn]);
;     *(u32x4*)(Wt + (size_t)(nt * 64 + nn) * K + kt * 64 + cch * 8) = mk4(pk[0], pk[1], pk[2], pk[3]);
;   }
.Lwc_last0:
	s_waitcnt vmcnt(0)
	ds_write_b128 v67, v[6:9] offset:0
	ds_write_b128 v67, v[10:13] offset:4352
	ds_write_b128 v67, v[14:17] offset:8704
	ds_write_b128 v67, v[18:21] offset:13056
	s_waitcnt lgkmcnt(0)
	s_barrier
	ds_read_b32 v38, v68 offset:0
	ds_read_b32 v39, v68 offset:272
	ds_read_b32 v40, v68 offset:544
	ds_read_b32 v41, v68 offset:816
	ds_read_b32 v42, v68 offset:1088
	ds_read_b32 v43, v68 offset:1360
	ds_read_b32 v44, v68 offset:1632
	ds_read_b32 v45, v68 offset:1904
	ds_read_b32 v46, v68 offset:2176
	ds_read_b32 v47, v68 offset:2448
	ds_read_b32 v48, v68 offset:2720
	ds_read_b32 v49, v68 offset:2992
	ds_read_b32 v50, v68 offset:3264
	ds_read_b32 v51, v68 offset:3536
	ds_read_b32 v52, v68 offset:3808
	ds_read_b32 v53, v68 offset:4080
	v_mul_u32_u24_e32 v73, s32, v69
	v_add_u32_e32 v73, v73, v70
	s_waitcnt lgkmcnt(0)
	v_cvt_pk_bf16_f32 v54, v38, v39
	v_cvt_pk_bf16_f32 v55, v40, v41
	v_cvt_pk_bf16_f32 v56, v42, v43
	v_cvt_pk_bf16_f32 v57, v44, v45
	v_cvt_pk_bf16_f32 v58, v46, v47
	v_cvt_pk_bf16_f32 v59, v48, v49
	v_cvt_pk_bf16_f32 v60, v50, v51
	v_cvt_pk_bf16_f32 v61, v52, v53
	global_store_dwordx4 v73, v[54:57], s[30:31]
	global_store_dwordx4 v73, v[58:61], s[30:31] offset:16
	s_branch .Lwc_exit
.Lwc_last1:
	s_waitcnt vmcnt(0)
	ds_write_b128 v67, v[22:25] offset:17408
	ds_write_b128 v67, v[26:29] offset:21760
	ds_write_b128 v67, v[30:33] offset:26112
	ds_write_b128 v67, v[34:37] offset:30464
	s_waitcnt lgkmcnt(0)
	s_barrier
	ds_read_b32 v38, v68 offset:17408
	ds_read_b32 v39, v68 offset:17680
	ds_read_b32 v40, v68 offset:17952
	ds_read_b32 v41, v68 offset:18224
	ds_read_b32 v42, v68 offset:18496
	ds_read_b32 v43, v68 offset:18768
	ds_read_b32 v44, v68 offset:19040
	ds_read_b32 v45, v68 offset:19312
	ds_read_b32 v46, v68 offset:19584
	ds_read_b32 v47, v68 offset:19856
	ds_read_b32 v48, v68 offset:20128
	ds_read_b32 v49, v68 offset:20400
	ds_read_b32 v50, v68 offset:20672
	ds_read_b32 v51, v68 offset:20944
	ds_read_b32 v52, v68 offset:21216
	ds_read_b32 v53, v68 offset:21488
	v_mul_u32_u24_e32 v73, s40, v69
	v_add_u32_e32 v73, v73, v70
	s_waitcnt lgkmcnt(0)
	v_cvt_pk_bf16_f32 v54, v38, v39
	v_cvt_pk_bf16_f32 v55, v40, v41
	v_cvt_pk_bf16_f32 v56, v42, v43
	v_cvt_pk_bf16_f32 v57, v44, v45
	v_cvt_pk_bf16_f32 v58, v46, v47
	v_cvt_pk_bf16_f32 v59, v48, v49
	v_cvt_pk_bf16_f32 v60, v50, v51
	v_cvt_pk_bf16_f32 v61, v52, v53
	global_store_dwordx4 v73, v[54:57], s[38:39]
	global_store_dwordx4 v73, v[58:61], s[38:39] offset:16
.Lwc_exit:
	s_waitcnt vmcnt(0) lgkmcnt(0)
	s_barrier
	v_readlane_b32 s0, v255, 0
	v_readlane_b32 s1, v255, 1
	v_readlane_b32 s2, v255, 2
	v_readlane_b32 s3, v255, 3
	v_readlane_b32 s4, v255, 4
	v_readlane_b32 s5, v255, 5
	v_readlane_b32 s6, v255, 6
	v_readlane_b32 s7, v255, 7
	v_readlane_b32 s8, v255, 8
	v_readlane_b32 s9, v255, 9
	v_readlane_b32 s10, v255, 10
	v_readlane_b32 s11, v255, 11
	v_readlane_b32 s12, v255, 12
	v_readlane_b32 s13, v255, 13
	v_readlane_b32 s14, v255, 14
	v_readlane_b32 s15, v255, 15
	v_readlane_b32 s16, v255, 16
	v_readlane_b32 s17, v255, 17
	v_readlane_b32 s18, v255, 18
	v_readlane_b32 s19, v255, 19
	v_readlane_b32 s20, v255, 20
	v_readlane_b32 s21, v255, 21
	v_readlane_b32 s22, v255, 22
	v_readlane_b32 s23, v255, 23
	v_readlane_b32 s24, v255, 24
	v_readlane_b32 s25, v255, 25
	v_readlane_b32 s26, v255, 26
	v_readlane_b32 s27, v255, 27
	v_readlane_b32 s28, v255, 28
	v_readlane_b32 s29, v255, 29
	v_readlane_b32 s30, v255, 30
	v_readlane_b32 s31, v255, 31
	v_readlane_b32 s32, v255, 32
	v_readlane_b32 s33, v255, 33
	v_readlane_b32 s34, v255, 34
	v_readlane_b32 s35, v255, 35
	v_readlane_b32 s36, v255, 36
	v_readlane_b32 s37, v255, 37
	v_readlane_b32 s38, v255, 38
	v_readlane_b32 s39, v255, 39
	v_readlane_b32 s40, v255, 40
	v_readlane_b32 s41, v255, 41
	v_readlane_b32 s42, v255, 42
	v_readlane_b32 s43, v255, 43
	v_readlane_b32 s44, v255, 44
	v_readlane_b32 s45, v255, 45
	v_readlane_b32 s46, v255, 46
	v_readlane_b32 s47, v255, 47
	v_readlane_b32 s48, v255, 48
	v_readlane_b32 s49, v255, 49
	v_readlane_b32 s50, v255, 50
	v_readlane_b32 s51, v255, 51
	v_readlane_b32 s52, v255, 52
	v_readlane_b32 s53, v255, 53
	v_readlane_b32 s54, v255, 54
	v_readlane_b32 s55, v255, 55
	v_readlane_b32 s56, v255, 56
	v_readlane_b32 s57, v255, 57
	v_readlane_b32 s58, v255, 58
	v_readlane_b32 s59, v255, 59
	v_readlane_b32 s60, v255, 60
	v_readlane_b32 s61, v255, 61
	v_readlane_b32 s62, v255, 62
	v_readlane_b32 s63, v255, 63
	v_readlane_b32 s64, v254, 0
	v_readlane_b32 s65, v254, 1
	v_readlane_b32 s66, v254, 2
	v_readlane_b32 s67, v254, 3
	v_readlane_b32 s68, v254, 4
	v_readlane_b32 s69, v254, 5
	v_readlane_b32 s70, v254, 6
	v_readlane_b32 s71, v254, 7
	v_readlane_b32 s72, v254, 8
	v_readlane_b32 s73, v254, 9
	v_readlane_b32 s74, v254, 10
	v_readlane_b32 s75, v254, 11
	v_readlane_b32 s76, v254, 12
	v_readlane_b32 s77, v254, 13
	v_readlane_b32 s78, v254, 14
	v_readlane_b32 s79, v254, 15
	v_readlane_b32 s80, v254, 16
	v_readlane_b32 s81, v254, 17
	v_readlane_b32 s82, v254, 18
	v_readlane_b32 s83, v254, 19
	v_readlane_b32 s84, v254, 20
	v_readlane_b32 s85, v254, 21
